# in-proj epilogue: RoPE cos/sin loads of a row group issued together (was two dependent load stages per row group)
# baseline (speedup 1.0000x reference)
; __device__ __forceinline__ unsigned cvt_pk_bf16(float lo, float hi) { const f32x2_t v = {lo, hi}; const bf16x2_t b = __builtin_convertvector(v, bf16x2_t); return __builtin_bit_cast(unsigned, b); }
;     __device__ __forceinline__ void operator()(const Acc& acc, const Unit& u, int wr, int wc, int fr, int fq) const {
;     ...
;                     if (wc < 2) {
; #pragma unroll
;                         for (int n = 0; n < 2; ++n) { const int d = n * 16 + fq * 4;
;                             const f32x4 cs = *(const f32x4*)(rp + d), sn = *(const f32x4*)(rp + 32 + d);
;                             const f32x4 x1 = acc[ai][0][m][n], x2 = acc[ai][1][m][n];
;                             const f32x4 o1 = x1 * cs - x2 * sn, o2 = x2 * cs + x1 * sn;
;                             bf16_t* kp = Kb + (size_t)row * 128 + wc * 64 + d;
;                             *(u32x2*)kp = (u32x2){cvt_pk_bf16(o1[0], o1[1]), cvt_pk_bf16(o1[2], o1[3])};
;                             *(u32x2*)(kp + 32) = (u32x2){cvt_pk_bf16(o2[0], o2[1]), cvt_pk_bf16(o2[2], o2[3])};
;                             if (keep) { float* op = out + okoff + (orow * 2 + wc) * 64 + d; *(f32x4*)op = o1; *(f32x4*)(op + 32) = o2; } }
.LBB0_453:
	s_and_b64 vcc, exec, s[4:5]
	s_cbranch_vccz .LBB0_459
	v_ashrrev_i32_e32 v145, 31, v144
	v_lshl_add_u64 v[184:185], v[144:145], 2, v[154:155]
	global_load_dwordx4 v[132:135], v[184:185], off offset:128
	global_load_dwordx4 v[208:211], v[184:185], off
	global_load_dwordx4 v[216:219], v[184:185], off offset:192
	global_load_dwordx4 v[220:223], v[184:185], off offset:64
	v_ashrrev_i32_e32 v153, 31, v152
	v_lshl_add_u64 v[186:187], v[130:131], 0, v[128:129]
	v_lshlrev_b64 v[128:129], 8, v[152:153]
	v_lshl_add_u64 v[128:129], s[30:31], 0, v[128:129]
	v_lshl_add_u64 v[158:159], v[144:145], 1, v[128:129]
	v_lshl_add_u64 v[186:187], v[186:187], 2, s[10:11]
	s_waitcnt vmcnt(0)
	v_pk_mul_f32 v[128:129], v[122:123], v[134:135]
	v_pk_mul_f32 v[212:213], v[120:121], v[132:133]
	v_pk_mul_f32 v[134:135], v[126:127], v[134:135]
	v_pk_mul_f32 v[132:133], v[124:125], v[132:133]
	v_pk_fma_f32 v[130:131], v[126:127], v[210:211], v[128:129] neg_lo:[0,0,1] neg_hi:[0,0,1]
	v_pk_fma_f32 v[128:129], v[124:125], v[208:209], v[212:213] neg_lo:[0,0,1] neg_hi:[0,0,1]
	v_pk_fma_f32 v[134:135], v[122:123], v[210:211], v[134:135]
	v_pk_fma_f32 v[132:133], v[120:121], v[208:209], v[132:133]
	v_cvt_pk_bf16_f32 v208, v128, v129
	v_cvt_pk_bf16_f32 v209, v130, v131
	v_cvt_pk_bf16_f32 v210, v132, v133
	v_cvt_pk_bf16_f32 v211, v134, v135
	global_store_dwordx2 v[158:159], v[208:209], off
	global_store_dwordx2 v[158:159], v[210:211], off offset:64
	s_and_saveexec_b64 s[4:5], s[2:3]
	s_cbranch_execz .LBB0_456
	v_lshl_add_u64 v[208:209], v[186:187], 0, v[156:157]
	s_lshl_b32 s74, s66, 2
	v_lshl_add_u64 v[208:209], v[208:209], 0, s[74:75]
	v_lshl_add_u64 v[208:209], v[144:145], 2, v[208:209]
	global_store_dwordx4 v[208:209], v[128:131], off
	global_store_dwordx4 v[208:209], v[132:135], off offset:128
.LBB0_456:
	s_or_b64 exec, exec, s[4:5]
	v_pk_mul_f32 v[184:185], v[114:115], v[218:219]
	v_pk_mul_f32 v[208:209], v[112:113], v[216:217]
	v_pk_mul_f32 v[210:211], v[118:119], v[218:219]
	v_pk_mul_f32 v[212:213], v[116:117], v[216:217]
	v_pk_fma_f32 v[218:219], v[118:119], v[222:223], v[184:185] neg_lo:[0,0,1] neg_hi:[0,0,1]
	v_pk_fma_f32 v[216:217], v[116:117], v[220:221], v[208:209] neg_lo:[0,0,1] neg_hi:[0,0,1]
	v_pk_fma_f32 v[222:223], v[114:115], v[222:223], v[210:211]
	v_pk_fma_f32 v[220:221], v[112:113], v[220:221], v[212:213]
	v_cvt_pk_bf16_f32 v184, v216, v217
	v_cvt_pk_bf16_f32 v185, v218, v219
	v_cvt_pk_bf16_f32 v208, v220, v221
	v_cvt_pk_bf16_f32 v209, v222, v223
	global_store_dwordx2 v[158:159], v[184:185], off offset:32
	global_store_dwordx2 v[158:159], v[208:209], off offset:96
	s_and_saveexec_b64 s[4:5], s[2:3]
	s_cbranch_execz .LBB0_458
	v_lshl_add_u64 v[156:157], v[186:187], 0, v[156:157]
	s_lshl_b32 s74, s66, 2
	v_lshl_add_u64 v[156:157], v[156:157], 0, s[74:75]
	v_lshl_add_u64 v[156:157], v[144:145], 2, v[156:157]
	global_store_dwordx4 v[156:157], v[216:219], off offset:64
	global_store_dwordx4 v[156:157], v[220:223], off offset:192
.LBB0_458:
	s_or_b64 exec, exec, s[4:5]
	v_mov_b32_e32 v128, v216
	v_mov_b32_e32 v129, v217
	v_mov_b32_e32 v130, v218
	v_mov_b32_e32 v131, v219
	v_mov_b32_e32 v132, v220
	v_mov_b32_e32 v133, v221
	v_mov_b32_e32 v134, v222
	v_mov_b32_e32 v135, v223

; __device__ __forceinline__ unsigned cvt_pk_bf16(float lo, float hi) { const f32x2_t v = {lo, hi}; const bf16x2_t b = __builtin_convertvector(v, bf16x2_t); return __builtin_bit_cast(unsigned, b); }
;     __device__ __forceinline__ void operator()(const Acc& acc, const Unit& u, int wr, int wc, int fr, int fq) const {
;     ...
;                 if (u.pn <= 1) {
; #pragma unroll
;                     for (int n = 0; n < 2; ++n) { const int d = n * 16 + fq * 4;
;                         const f32x4 cs = *(const f32x4*)(rp + d), sn = *(const f32x4*)(rp + 32 + d);
;                         const f32x4 x1 = acc[ai][0][m][n], x2 = acc[ai][1][m][n];
;                         const f32x4 o1 = (x1 * cs - x2 * sn) * 0.125f, o2 = (x2 * cs + x1 * sn) * 0.125f;
;                         bf16_t* qp = Q + (size_t)row * 512 + (u.pn * 4 + wc) * 64 + d;
;                         *(u32x2*)qp = (u32x2){cvt_pk_bf16(o1[0], o1[1]), cvt_pk_bf16(o1[2], o1[3])};
;                         *(u32x2*)(qp + 32) = (u32x2){cvt_pk_bf16(o2[0], o2[1]), cvt_pk_bf16(o2[2], o2[3])}; }
.LBB0_460:
	s_lshl_b32 s2, s42, 8
	s_or_b32 s44, s2, s66
	s_ashr_i32 s45, s44, 31
	s_and_b64 vcc, exec, s[6:7]
	v_ashrrev_i32_e32 v145, 31, v144
	s_cbranch_vccz .LBB0_462
	v_lshl_add_u64 v[154:155], v[144:145], 2, v[154:155]
	global_load_dwordx4 v[128:131], v[154:155], off offset:128
	global_load_dwordx4 v[132:135], v[154:155], off
	global_load_dwordx4 v[208:211], v[154:155], off offset:192
	global_load_dwordx4 v[212:215], v[154:155], off offset:64
	v_ashrrev_i32_e32 v153, 31, v152
	v_lshlrev_b64 v[156:157], 10, v[152:153]
	v_lshl_add_u64 v[156:157], s[14:15], 0, v[156:157]
	v_lshl_add_u64 v[156:157], s[44:45], 1, v[156:157]
	v_lshl_add_u64 v[156:157], v[144:145], 1, v[156:157]
	s_waitcnt vmcnt(0)
	v_pk_mul_f32 v[158:159], v[122:123], v[130:131]
	v_pk_mul_f32 v[184:185], v[120:121], v[128:129]
	v_pk_mul_f32 v[130:131], v[126:127], v[130:131]
	v_pk_mul_f32 v[128:129], v[124:125], v[128:129]
	v_pk_fma_f32 v[126:127], v[126:127], v[134:135], v[158:159] neg_lo:[0,0,1] neg_hi:[0,0,1]
	v_pk_fma_f32 v[124:125], v[124:125], v[132:133], v[184:185] neg_lo:[0,0,1] neg_hi:[0,0,1]
	v_pk_fma_f32 v[122:123], v[122:123], v[134:135], v[130:131]
	v_pk_fma_f32 v[120:121], v[120:121], v[132:133], v[128:129]
	v_pk_mul_f32 v[126:127], v[126:127], s[88:89] op_sel_hi:[1,0]
	v_pk_mul_f32 v[124:125], v[124:125], s[88:89] op_sel_hi:[1,0]
	v_pk_mul_f32 v[122:123], v[122:123], s[88:89] op_sel_hi:[1,0]
	v_pk_mul_f32 v[120:121], v[120:121], s[88:89] op_sel_hi:[1,0]
	v_cvt_pk_bf16_f32 v124, v124, v125
	v_cvt_pk_bf16_f32 v125, v126, v127
	v_cvt_pk_bf16_f32 v120, v120, v121
	v_cvt_pk_bf16_f32 v121, v122, v123
	global_store_dwordx2 v[156:157], v[124:125], off
	global_store_dwordx2 v[156:157], v[120:121], off offset:64
	v_pk_mul_f32 v[128:129], v[114:115], v[210:211]
	v_pk_mul_f32 v[130:131], v[112:113], v[208:209]
	v_pk_mul_f32 v[210:211], v[118:119], v[210:211]
	v_pk_mul_f32 v[208:209], v[116:117], v[208:209]
	v_pk_fma_f32 v[118:119], v[118:119], v[214:215], v[128:129] neg_lo:[0,0,1] neg_hi:[0,0,1]
	v_pk_fma_f32 v[116:117], v[116:117], v[212:213], v[130:131] neg_lo:[0,0,1] neg_hi:[0,0,1]
	v_pk_fma_f32 v[114:115], v[114:115], v[214:215], v[210:211]
	v_pk_fma_f32 v[112:113], v[112:113], v[212:213], v[208:209]
	v_pk_mul_f32 v[118:119], v[118:119], s[88:89] op_sel_hi:[1,0]
	v_pk_mul_f32 v[116:117], v[116:117], s[88:89] op_sel_hi:[1,0]
	v_pk_mul_f32 v[114:115], v[114:115], s[88:89] op_sel_hi:[1,0]
	v_pk_mul_f32 v[112:113], v[112:113], s[88:89] op_sel_hi:[1,0]
	v_cvt_pk_bf16_f32 v116, v116, v117
	v_cvt_pk_bf16_f32 v117, v118, v119
	v_cvt_pk_bf16_f32 v112, v112, v113
	v_cvt_pk_bf16_f32 v113, v114, v115
	global_store_dwordx2 v[156:157], v[116:117], off offset:32
	global_store_dwordx2 v[156:157], v[112:113], off offset:96
	v_mov_b32_e32 v120, v208
	v_mov_b32_e32 v121, v209
	v_mov_b32_e32 v122, v210
	v_mov_b32_e32 v123, v211
	v_mov_b32_e32 v124, v212
	v_mov_b32_e32 v125, v213
	v_mov_b32_e32 v126, v214
	v_mov_b32_e32 v127, v215

; __device__ __forceinline__ unsigned cvt_pk_bf16(float lo, float hi) { const f32x2_t v = {lo, hi}; const bf16x2_t b = __builtin_convertvector(v, bf16x2_t); return __builtin_bit_cast(unsigned, b); }
;     __device__ __forceinline__ void operator()(const Acc& acc, const Unit& u, int wr, int wc, int fr, int fq) const {
;     ...
;                     if (wc < 2) {
; #pragma unroll
;                         for (int n = 0; n < 2; ++n) { const int d = n * 16 + fq * 4;
;                             const f32x4 cs = *(const f32x4*)(rp + d), sn = *(const f32x4*)(rp + 32 + d);
;                             const f32x4 x1 = acc[ai][0][m][n], x2 = acc[ai][1][m][n];
;                             const f32x4 o1 = x1 * cs - x2 * sn, o2 = x2 * cs + x1 * sn;
;                             bf16_t* kp = Kb + (size_t)row * 128 + wc * 64 + d;
;                             *(u32x2*)kp = (u32x2){cvt_pk_bf16(o1[0], o1[1]), cvt_pk_bf16(o1[2], o1[3])};
;                             *(u32x2*)(kp + 32) = (u32x2){cvt_pk_bf16(o2[0], o2[1]), cvt_pk_bf16(o2[2], o2[3])};
;                             if (keep) { float* op = out + okoff + (orow * 2 + wc) * 64 + d; *(f32x4*)op = o1; *(f32x4*)(op + 32) = o2; } }
.LBB0_502:
	s_and_b64 vcc, exec, s[6:7]
	s_cbranch_vccz .LBB0_508
	v_lshl_add_u64 v[128:129], v[144:145], 2, v[122:123]
	global_load_dwordx4 v[116:119], v[128:129], off offset:128
	global_load_dwordx4 v[130:133], v[128:129], off
	global_load_dwordx4 v[208:211], v[128:129], off offset:192
	global_load_dwordx4 v[212:215], v[128:129], off offset:64
	v_ashrrev_i32_e32 v121, 31, v120
	v_lshl_add_u64 v[134:135], v[114:115], 0, v[112:113]
	v_lshlrev_b64 v[112:113], 8, v[120:121]
	v_lshl_add_u64 v[112:113], s[30:31], 0, v[112:113]
	v_lshl_add_u64 v[126:127], v[144:145], 1, v[112:113]
	s_waitcnt vmcnt(0)
	v_pk_mul_f32 v[112:113], v[106:107], v[118:119]
	v_pk_mul_f32 v[154:155], v[104:105], v[116:117]
	v_pk_mul_f32 v[118:119], v[110:111], v[118:119]
	v_pk_mul_f32 v[116:117], v[108:109], v[116:117]
	v_pk_fma_f32 v[114:115], v[110:111], v[132:133], v[112:113] neg_lo:[0,0,1] neg_hi:[0,0,1]
	v_pk_fma_f32 v[112:113], v[108:109], v[130:131], v[154:155] neg_lo:[0,0,1] neg_hi:[0,0,1]
	v_pk_fma_f32 v[118:119], v[106:107], v[132:133], v[118:119]
	v_pk_fma_f32 v[116:117], v[104:105], v[130:131], v[116:117]
	v_cvt_pk_bf16_f32 v130, v112, v113
	v_cvt_pk_bf16_f32 v131, v114, v115
	v_cvt_pk_bf16_f32 v132, v116, v117
	v_cvt_pk_bf16_f32 v133, v118, v119
	global_store_dwordx2 v[126:127], v[130:131], off
	global_store_dwordx2 v[126:127], v[132:133], off offset:64
	v_lshl_add_u64 v[130:131], v[134:135], 2, s[10:11]
	s_and_saveexec_b64 s[6:7], s[4:5]
	s_cbranch_execz .LBB0_505
	v_lshl_add_u64 v[132:133], v[130:131], 0, v[124:125]
	s_lshl_b32 s74, s66, 2
	v_lshl_add_u64 v[132:133], v[132:133], 0, s[74:75]
	v_lshl_add_u64 v[132:133], v[144:145], 2, v[132:133]
	global_store_dwordx4 v[132:133], v[112:115], off
	global_store_dwordx4 v[132:133], v[116:119], off offset:128
.LBB0_505:
	s_or_b64 exec, exec, s[6:7]
	v_pk_mul_f32 v[128:129], v[98:99], v[210:211]
	v_pk_mul_f32 v[132:133], v[96:97], v[208:209]
	v_pk_mul_f32 v[134:135], v[102:103], v[210:211]
	v_pk_mul_f32 v[154:155], v[100:101], v[208:209]
	v_pk_fma_f32 v[210:211], v[102:103], v[214:215], v[128:129] neg_lo:[0,0,1] neg_hi:[0,0,1]
	v_pk_fma_f32 v[208:209], v[100:101], v[212:213], v[132:133] neg_lo:[0,0,1] neg_hi:[0,0,1]
	v_pk_fma_f32 v[214:215], v[98:99], v[214:215], v[134:135]
	v_pk_fma_f32 v[212:213], v[96:97], v[212:213], v[154:155]
	v_cvt_pk_bf16_f32 v128, v208, v209
	v_cvt_pk_bf16_f32 v129, v210, v211
	v_cvt_pk_bf16_f32 v132, v212, v213
	v_cvt_pk_bf16_f32 v133, v214, v215
	global_store_dwordx2 v[126:127], v[128:129], off offset:32
	global_store_dwordx2 v[126:127], v[132:133], off offset:96
	s_and_saveexec_b64 s[6:7], s[4:5]
	s_cbranch_execz .LBB0_507
	v_lshl_add_u64 v[124:125], v[130:131], 0, v[124:125]
	s_lshl_b32 s74, s66, 2
	v_lshl_add_u64 v[124:125], v[124:125], 0, s[74:75]
	v_lshl_add_u64 v[124:125], v[144:145], 2, v[124:125]
	global_store_dwordx4 v[124:125], v[208:211], off offset:64
	global_store_dwordx4 v[124:125], v[212:215], off offset:192
.LBB0_507:
	s_or_b64 exec, exec, s[6:7]
	v_mov_b32_e32 v112, v208
	v_mov_b32_e32 v113, v209
	v_mov_b32_e32 v114, v210
	v_mov_b32_e32 v115, v211
	v_mov_b32_e32 v116, v212
	v_mov_b32_e32 v117, v213
	v_mov_b32_e32 v118, v214
	v_mov_b32_e32 v119, v215

; __device__ __forceinline__ unsigned cvt_pk_bf16(float lo, float hi) { const f32x2_t v = {lo, hi}; const bf16x2_t b = __builtin_convertvector(v, bf16x2_t); return __builtin_bit_cast(unsigned, b); }
;     __device__ __forceinline__ void operator()(const Acc& acc, const Unit& u, int wr, int wc, int fr, int fq) const {
;     ...
;                 if (u.pn <= 1) {
; #pragma unroll
;                     for (int n = 0; n < 2; ++n) { const int d = n * 16 + fq * 4;
;                         const f32x4 cs = *(const f32x4*)(rp + d), sn = *(const f32x4*)(rp + 32 + d);
;                         const f32x4 x1 = acc[ai][0][m][n], x2 = acc[ai][1][m][n];
;                         const f32x4 o1 = (x1 * cs - x2 * sn) * 0.125f, o2 = (x2 * cs + x1 * sn) * 0.125f;
;                         bf16_t* qp = Q + (size_t)row * 512 + (u.pn * 4 + wc) * 64 + d;
;                         *(u32x2*)qp = (u32x2){cvt_pk_bf16(o1[0], o1[1]), cvt_pk_bf16(o1[2], o1[3])};
;                         *(u32x2*)(qp + 32) = (u32x2){cvt_pk_bf16(o2[0], o2[1]), cvt_pk_bf16(o2[2], o2[3])}; }
.LBB0_509:
	s_and_b64 vcc, exec, s[46:47]
	s_cbranch_vccz .LBB0_511
	v_lshl_add_u64 v[122:123], v[144:145], 2, v[122:123]
	global_load_dwordx4 v[112:115], v[122:123], off offset:128
	global_load_dwordx4 v[116:119], v[122:123], off
	global_load_dwordx4 v[208:211], v[122:123], off offset:192
	global_load_dwordx4 v[212:215], v[122:123], off offset:64
	v_ashrrev_i32_e32 v121, 31, v120
	v_lshlrev_b64 v[120:121], 10, v[120:121]
	v_lshl_add_u64 v[120:121], s[14:15], 0, v[120:121]
	v_lshl_add_u64 v[120:121], s[44:45], 1, v[120:121]
	v_lshl_add_u64 v[120:121], v[144:145], 1, v[120:121]
	s_waitcnt vmcnt(0)
	v_pk_mul_f32 v[124:125], v[106:107], v[114:115]
	v_pk_mul_f32 v[126:127], v[104:105], v[112:113]
	v_pk_mul_f32 v[114:115], v[110:111], v[114:115]
	v_pk_mul_f32 v[112:113], v[108:109], v[112:113]
	v_pk_fma_f32 v[110:111], v[110:111], v[118:119], v[124:125] neg_lo:[0,0,1] neg_hi:[0,0,1]
	v_pk_fma_f32 v[108:109], v[108:109], v[116:117], v[126:127] neg_lo:[0,0,1] neg_hi:[0,0,1]
	v_pk_fma_f32 v[106:107], v[106:107], v[118:119], v[114:115]
	v_pk_fma_f32 v[104:105], v[104:105], v[116:117], v[112:113]
	v_pk_mul_f32 v[110:111], v[110:111], s[88:89] op_sel_hi:[1,0]
	v_pk_mul_f32 v[108:109], v[108:109], s[88:89] op_sel_hi:[1,0]
	v_pk_mul_f32 v[106:107], v[106:107], s[88:89] op_sel_hi:[1,0]
	v_pk_mul_f32 v[104:105], v[104:105], s[88:89] op_sel_hi:[1,0]
	v_cvt_pk_bf16_f32 v108, v108, v109
	v_cvt_pk_bf16_f32 v109, v110, v111
	v_cvt_pk_bf16_f32 v104, v104, v105
	v_cvt_pk_bf16_f32 v105, v106, v107
	global_store_dwordx2 v[120:121], v[108:109], off
	global_store_dwordx2 v[120:121], v[104:105], off offset:64
	v_pk_mul_f32 v[112:113], v[98:99], v[210:211]
	v_pk_mul_f32 v[114:115], v[96:97], v[208:209]
	v_pk_mul_f32 v[210:211], v[102:103], v[210:211]
	v_pk_mul_f32 v[208:209], v[100:101], v[208:209]
	v_pk_fma_f32 v[102:103], v[102:103], v[214:215], v[112:113] neg_lo:[0,0,1] neg_hi:[0,0,1]
	v_pk_fma_f32 v[100:101], v[100:101], v[212:213], v[114:115] neg_lo:[0,0,1] neg_hi:[0,0,1]
	v_pk_fma_f32 v[98:99], v[98:99], v[214:215], v[210:211]
	v_pk_fma_f32 v[96:97], v[96:97], v[212:213], v[208:209]
	v_pk_mul_f32 v[102:103], v[102:103], s[88:89] op_sel_hi:[1,0]
	v_pk_mul_f32 v[100:101], v[100:101], s[88:89] op_sel_hi:[1,0]
	v_pk_mul_f32 v[98:99], v[98:99], s[88:89] op_sel_hi:[1,0]
	v_pk_mul_f32 v[96:97], v[96:97], s[88:89] op_sel_hi:[1,0]
	v_cvt_pk_bf16_f32 v100, v100, v101
	v_cvt_pk_bf16_f32 v101, v102, v103
	v_cvt_pk_bf16_f32 v96, v96, v97
	v_cvt_pk_bf16_f32 v97, v98, v99
	global_store_dwordx2 v[120:121], v[100:101], off offset:32
	global_store_dwordx2 v[120:121], v[96:97], off offset:96
	v_mov_b32_e32 v104, v208
	v_mov_b32_e32 v105, v209
	v_mov_b32_e32 v106, v210
	v_mov_b32_e32 v107, v211
	v_mov_b32_e32 v108, v212
	v_mov_b32_e32 v109, v213
	v_mov_b32_e32 v110, v214
	v_mov_b32_e32 v111, v215

; __device__ __forceinline__ unsigned cvt_pk_bf16(float lo, float hi) { const f32x2_t v = {lo, hi}; const bf16x2_t b = __builtin_convertvector(v, bf16x2_t); return __builtin_bit_cast(unsigned, b); }
;     __device__ __forceinline__ void operator()(const Acc& acc, const Unit& u, int wr, int wc, int fr, int fq) const {
;     ...
;                     if (wc < 2) {
; #pragma unroll
;                         for (int n = 0; n < 2; ++n) { const int d = n * 16 + fq * 4;
;                             const f32x4 cs = *(const f32x4*)(rp + d), sn = *(const f32x4*)(rp + 32 + d);
;                             const f32x4 x1 = acc[ai][0][m][n], x2 = acc[ai][1][m][n];
;                             const f32x4 o1 = x1 * cs - x2 * sn, o2 = x2 * cs + x1 * sn;
;                             bf16_t* kp = Kb + (size_t)row * 128 + wc * 64 + d;
;                             *(u32x2*)kp = (u32x2){cvt_pk_bf16(o1[0], o1[1]), cvt_pk_bf16(o1[2], o1[3])};
;                             *(u32x2*)(kp + 32) = (u32x2){cvt_pk_bf16(o2[0], o2[1]), cvt_pk_bf16(o2[2], o2[3])};
;                             if (keep) { float* op = out + okoff + (orow * 2 + wc) * 64 + d; *(f32x4*)op = o1; *(f32x4*)(op + 32) = o2; } }
.LBB0_551:
	s_and_b64 vcc, exec, s[6:7]
	s_cbranch_vccz .LBB0_557
	v_lshl_add_u64 v[112:113], v[144:145], 2, v[106:107]
	global_load_dwordx4 v[100:103], v[112:113], off offset:128
	global_load_dwordx4 v[114:117], v[112:113], off
	global_load_dwordx4 v[208:211], v[112:113], off offset:192
	global_load_dwordx4 v[212:215], v[112:113], off offset:64
	v_ashrrev_i32_e32 v105, 31, v104
	v_lshl_add_u64 v[118:119], v[98:99], 0, v[96:97]
	v_lshlrev_b64 v[96:97], 8, v[104:105]
	v_lshl_add_u64 v[96:97], s[30:31], 0, v[96:97]
	v_lshl_add_u64 v[110:111], v[144:145], 1, v[96:97]
	s_waitcnt vmcnt(0)
	v_pk_mul_f32 v[96:97], v[90:91], v[102:103]
	v_pk_mul_f32 v[120:121], v[88:89], v[100:101]
	v_pk_mul_f32 v[102:103], v[94:95], v[102:103]
	v_pk_mul_f32 v[100:101], v[92:93], v[100:101]
	v_pk_fma_f32 v[98:99], v[94:95], v[116:117], v[96:97] neg_lo:[0,0,1] neg_hi:[0,0,1]
	v_pk_fma_f32 v[96:97], v[92:93], v[114:115], v[120:121] neg_lo:[0,0,1] neg_hi:[0,0,1]
	v_pk_fma_f32 v[102:103], v[90:91], v[116:117], v[102:103]
	v_pk_fma_f32 v[100:101], v[88:89], v[114:115], v[100:101]
	v_cvt_pk_bf16_f32 v114, v96, v97
	v_cvt_pk_bf16_f32 v115, v98, v99
	v_cvt_pk_bf16_f32 v116, v100, v101
	v_cvt_pk_bf16_f32 v117, v102, v103
	global_store_dwordx2 v[110:111], v[114:115], off
	global_store_dwordx2 v[110:111], v[116:117], off offset:64
	v_lshl_add_u64 v[114:115], v[118:119], 2, s[10:11]
	s_and_saveexec_b64 s[6:7], s[4:5]
	s_cbranch_execz .LBB0_554
	v_lshl_add_u64 v[116:117], v[114:115], 0, v[108:109]
	s_lshl_b32 s74, s66, 2
	v_lshl_add_u64 v[116:117], v[116:117], 0, s[74:75]
	v_lshl_add_u64 v[116:117], v[144:145], 2, v[116:117]
	global_store_dwordx4 v[116:117], v[96:99], off
	global_store_dwordx4 v[116:117], v[100:103], off offset:128
.LBB0_554:
	s_or_b64 exec, exec, s[6:7]
	v_pk_mul_f32 v[112:113], v[82:83], v[210:211]
	v_pk_mul_f32 v[116:117], v[80:81], v[208:209]
	v_pk_mul_f32 v[118:119], v[86:87], v[210:211]
	v_pk_mul_f32 v[120:121], v[84:85], v[208:209]
	v_pk_fma_f32 v[210:211], v[86:87], v[214:215], v[112:113] neg_lo:[0,0,1] neg_hi:[0,0,1]
	v_pk_fma_f32 v[208:209], v[84:85], v[212:213], v[116:117] neg_lo:[0,0,1] neg_hi:[0,0,1]
	v_pk_fma_f32 v[214:215], v[82:83], v[214:215], v[118:119]
	v_pk_fma_f32 v[212:213], v[80:81], v[212:213], v[120:121]
	v_cvt_pk_bf16_f32 v112, v208, v209
	v_cvt_pk_bf16_f32 v113, v210, v211
	v_cvt_pk_bf16_f32 v116, v212, v213
	v_cvt_pk_bf16_f32 v117, v214, v215
	global_store_dwordx2 v[110:111], v[112:113], off offset:32
	global_store_dwordx2 v[110:111], v[116:117], off offset:96
	s_and_saveexec_b64 s[6:7], s[4:5]
	s_cbranch_execz .LBB0_556
	v_lshl_add_u64 v[108:109], v[114:115], 0, v[108:109]
	s_lshl_b32 s74, s66, 2
	v_lshl_add_u64 v[108:109], v[108:109], 0, s[74:75]
	v_lshl_add_u64 v[108:109], v[144:145], 2, v[108:109]
	global_store_dwordx4 v[108:109], v[208:211], off offset:64
	global_store_dwordx4 v[108:109], v[212:215], off offset:192
.LBB0_556:
	s_or_b64 exec, exec, s[6:7]
	v_mov_b32_e32 v96, v208
	v_mov_b32_e32 v97, v209
	v_mov_b32_e32 v98, v210
	v_mov_b32_e32 v99, v211
	v_mov_b32_e32 v100, v212
	v_mov_b32_e32 v101, v213
	v_mov_b32_e32 v102, v214
	v_mov_b32_e32 v103, v215

; __device__ __forceinline__ unsigned cvt_pk_bf16(float lo, float hi) { const f32x2_t v = {lo, hi}; const bf16x2_t b = __builtin_convertvector(v, bf16x2_t); return __builtin_bit_cast(unsigned, b); }
;     __device__ __forceinline__ void operator()(const Acc& acc, const Unit& u, int wr, int wc, int fr, int fq) const {
;     ...
;                 if (u.pn <= 1) {
; #pragma unroll
;                     for (int n = 0; n < 2; ++n) { const int d = n * 16 + fq * 4;
;                         const f32x4 cs = *(const f32x4*)(rp + d), sn = *(const f32x4*)(rp + 32 + d);
;                         const f32x4 x1 = acc[ai][0][m][n], x2 = acc[ai][1][m][n];
;                         const f32x4 o1 = (x1 * cs - x2 * sn) * 0.125f, o2 = (x2 * cs + x1 * sn) * 0.125f;
;                         bf16_t* qp = Q + (size_t)row * 512 + (u.pn * 4 + wc) * 64 + d;
;                         *(u32x2*)qp = (u32x2){cvt_pk_bf16(o1[0], o1[1]), cvt_pk_bf16(o1[2], o1[3])};
;                         *(u32x2*)(qp + 32) = (u32x2){cvt_pk_bf16(o2[0], o2[1]), cvt_pk_bf16(o2[2], o2[3])}; }
.LBB0_558:
	s_and_b64 vcc, exec, s[46:47]
	s_cbranch_vccz .LBB0_560
	v_lshl_add_u64 v[106:107], v[144:145], 2, v[106:107]
	global_load_dwordx4 v[96:99], v[106:107], off offset:128
	global_load_dwordx4 v[100:103], v[106:107], off
	global_load_dwordx4 v[208:211], v[106:107], off offset:192
	global_load_dwordx4 v[212:215], v[106:107], off offset:64
	v_ashrrev_i32_e32 v105, 31, v104
	v_lshlrev_b64 v[104:105], 10, v[104:105]
	v_lshl_add_u64 v[104:105], s[14:15], 0, v[104:105]
	v_lshl_add_u64 v[104:105], s[44:45], 1, v[104:105]
	v_lshl_add_u64 v[104:105], v[144:145], 1, v[104:105]
	s_waitcnt vmcnt(0)
	v_pk_mul_f32 v[108:109], v[90:91], v[98:99]
	v_pk_mul_f32 v[110:111], v[88:89], v[96:97]
	v_pk_mul_f32 v[98:99], v[94:95], v[98:99]
	v_pk_mul_f32 v[96:97], v[92:93], v[96:97]
	v_pk_fma_f32 v[94:95], v[94:95], v[102:103], v[108:109] neg_lo:[0,0,1] neg_hi:[0,0,1]
	v_pk_fma_f32 v[92:93], v[92:93], v[100:101], v[110:111] neg_lo:[0,0,1] neg_hi:[0,0,1]
	v_pk_fma_f32 v[90:91], v[90:91], v[102:103], v[98:99]
	v_pk_fma_f32 v[88:89], v[88:89], v[100:101], v[96:97]
	v_pk_mul_f32 v[94:95], v[94:95], s[88:89] op_sel_hi:[1,0]
	v_pk_mul_f32 v[92:93], v[92:93], s[88:89] op_sel_hi:[1,0]
	v_pk_mul_f32 v[90:91], v[90:91], s[88:89] op_sel_hi:[1,0]
	v_pk_mul_f32 v[88:89], v[88:89], s[88:89] op_sel_hi:[1,0]
	v_cvt_pk_bf16_f32 v92, v92, v93
	v_cvt_pk_bf16_f32 v93, v94, v95
	v_cvt_pk_bf16_f32 v88, v88, v89
	v_cvt_pk_bf16_f32 v89, v90, v91
	global_store_dwordx2 v[104:105], v[92:93], off
	global_store_dwordx2 v[104:105], v[88:89], off offset:64
	v_pk_mul_f32 v[96:97], v[82:83], v[210:211]
	v_pk_mul_f32 v[98:99], v[80:81], v[208:209]
	v_pk_mul_f32 v[210:211], v[86:87], v[210:211]
	v_pk_mul_f32 v[208:209], v[84:85], v[208:209]
	v_pk_fma_f32 v[86:87], v[86:87], v[214:215], v[96:97] neg_lo:[0,0,1] neg_hi:[0,0,1]
	v_pk_fma_f32 v[84:85], v[84:85], v[212:213], v[98:99] neg_lo:[0,0,1] neg_hi:[0,0,1]
	v_pk_fma_f32 v[82:83], v[82:83], v[214:215], v[210:211]
	v_pk_fma_f32 v[80:81], v[80:81], v[212:213], v[208:209]
	v_pk_mul_f32 v[86:87], v[86:87], s[88:89] op_sel_hi:[1,0]
	v_pk_mul_f32 v[84:85], v[84:85], s[88:89] op_sel_hi:[1,0]
	v_pk_mul_f32 v[82:83], v[82:83], s[88:89] op_sel_hi:[1,0]
	v_pk_mul_f32 v[80:81], v[80:81], s[88:89] op_sel_hi:[1,0]
	v_cvt_pk_bf16_f32 v84, v84, v85
	v_cvt_pk_bf16_f32 v85, v86, v87
	v_cvt_pk_bf16_f32 v80, v80, v81
	v_cvt_pk_bf16_f32 v81, v82, v83
	global_store_dwordx2 v[104:105], v[84:85], off offset:32
	global_store_dwordx2 v[104:105], v[80:81], off offset:96
	v_mov_b32_e32 v88, v208
	v_mov_b32_e32 v89, v209
	v_mov_b32_e32 v90, v210
	v_mov_b32_e32 v91, v211
	v_mov_b32_e32 v92, v212
	v_mov_b32_e32 v93, v213
	v_mov_b32_e32 v94, v214
	v_mov_b32_e32 v95, v215

; __device__ __forceinline__ unsigned cvt_pk_bf16(float lo, float hi) { const f32x2_t v = {lo, hi}; const bf16x2_t b = __builtin_convertvector(v, bf16x2_t); return __builtin_bit_cast(unsigned, b); }
;     __device__ __forceinline__ void operator()(const Acc& acc, const Unit& u, int wr, int wc, int fr, int fq) const {
;     ...
;                     if (wc < 2) {
; #pragma unroll
;                         for (int n = 0; n < 2; ++n) { const int d = n * 16 + fq * 4;
;                             const f32x4 cs = *(const f32x4*)(rp + d), sn = *(const f32x4*)(rp + 32 + d);
;                             const f32x4 x1 = acc[ai][0][m][n], x2 = acc[ai][1][m][n];
;                             const f32x4 o1 = x1 * cs - x2 * sn, o2 = x2 * cs + x1 * sn;
;                             bf16_t* kp = Kb + (size_t)row * 128 + wc * 64 + d;
;                             *(u32x2*)kp = (u32x2){cvt_pk_bf16(o1[0], o1[1]), cvt_pk_bf16(o1[2], o1[3])};
;                             *(u32x2*)(kp + 32) = (u32x2){cvt_pk_bf16(o2[0], o2[1]), cvt_pk_bf16(o2[2], o2[3])};
;                             if (keep) { float* op = out + okoff + (orow * 2 + wc) * 64 + d; *(f32x4*)op = o1; *(f32x4*)(op + 32) = o2; } }
.LBB0_600:
	s_and_b64 vcc, exec, s[6:7]
	s_cbranch_vccz .LBB0_606
	v_lshl_add_u64 v[96:97], v[144:145], 2, v[90:91]
	global_load_dwordx4 v[84:87], v[96:97], off offset:128
	global_load_dwordx4 v[98:101], v[96:97], off
	global_load_dwordx4 v[208:211], v[96:97], off offset:192
	global_load_dwordx4 v[212:215], v[96:97], off offset:64
	v_ashrrev_i32_e32 v89, 31, v88
	v_lshl_add_u64 v[102:103], v[82:83], 0, v[80:81]
	v_lshlrev_b64 v[80:81], 8, v[88:89]
	v_lshl_add_u64 v[80:81], s[30:31], 0, v[80:81]
	v_lshl_add_u64 v[94:95], v[144:145], 1, v[80:81]
	s_waitcnt vmcnt(0)
	v_pk_mul_f32 v[80:81], v[74:75], v[86:87]
	v_pk_mul_f32 v[104:105], v[72:73], v[84:85]
	v_pk_mul_f32 v[86:87], v[78:79], v[86:87]
	v_pk_mul_f32 v[84:85], v[76:77], v[84:85]
	v_pk_fma_f32 v[82:83], v[78:79], v[100:101], v[80:81] neg_lo:[0,0,1] neg_hi:[0,0,1]
	v_pk_fma_f32 v[80:81], v[76:77], v[98:99], v[104:105] neg_lo:[0,0,1] neg_hi:[0,0,1]
	v_pk_fma_f32 v[86:87], v[74:75], v[100:101], v[86:87]
	v_pk_fma_f32 v[84:85], v[72:73], v[98:99], v[84:85]
	v_cvt_pk_bf16_f32 v98, v80, v81
	v_cvt_pk_bf16_f32 v99, v82, v83
	v_cvt_pk_bf16_f32 v100, v84, v85
	v_cvt_pk_bf16_f32 v101, v86, v87
	global_store_dwordx2 v[94:95], v[98:99], off
	global_store_dwordx2 v[94:95], v[100:101], off offset:64
	v_lshl_add_u64 v[98:99], v[102:103], 2, s[10:11]
	s_and_saveexec_b64 s[6:7], s[4:5]
	s_cbranch_execz .LBB0_603
	v_lshl_add_u64 v[100:101], v[98:99], 0, v[92:93]
	s_lshl_b32 s74, s66, 2
	v_lshl_add_u64 v[100:101], v[100:101], 0, s[74:75]
	v_lshl_add_u64 v[100:101], v[144:145], 2, v[100:101]
	global_store_dwordx4 v[100:101], v[80:83], off
	global_store_dwordx4 v[100:101], v[84:87], off offset:128
.LBB0_603:
	s_or_b64 exec, exec, s[6:7]
	v_pk_mul_f32 v[96:97], v[66:67], v[210:211]
	v_pk_mul_f32 v[100:101], v[64:65], v[208:209]
	v_pk_mul_f32 v[102:103], v[70:71], v[210:211]
	v_pk_mul_f32 v[104:105], v[68:69], v[208:209]
	v_pk_fma_f32 v[210:211], v[70:71], v[214:215], v[96:97] neg_lo:[0,0,1] neg_hi:[0,0,1]
	v_pk_fma_f32 v[208:209], v[68:69], v[212:213], v[100:101] neg_lo:[0,0,1] neg_hi:[0,0,1]
	v_pk_fma_f32 v[214:215], v[66:67], v[214:215], v[102:103]
	v_pk_fma_f32 v[212:213], v[64:65], v[212:213], v[104:105]
	v_cvt_pk_bf16_f32 v96, v208, v209
	v_cvt_pk_bf16_f32 v97, v210, v211
	v_cvt_pk_bf16_f32 v100, v212, v213
	v_cvt_pk_bf16_f32 v101, v214, v215
	global_store_dwordx2 v[94:95], v[96:97], off offset:32
	global_store_dwordx2 v[94:95], v[100:101], off offset:96
	s_and_saveexec_b64 s[6:7], s[4:5]
	s_cbranch_execz .LBB0_605
	v_lshl_add_u64 v[92:93], v[98:99], 0, v[92:93]
	s_lshl_b32 s74, s66, 2
	v_lshl_add_u64 v[92:93], v[92:93], 0, s[74:75]
	v_lshl_add_u64 v[92:93], v[144:145], 2, v[92:93]
	global_store_dwordx4 v[92:93], v[208:211], off offset:64
	global_store_dwordx4 v[92:93], v[212:215], off offset:192
.LBB0_605:
	s_or_b64 exec, exec, s[6:7]
	v_mov_b32_e32 v80, v208
	v_mov_b32_e32 v81, v209
	v_mov_b32_e32 v82, v210
	v_mov_b32_e32 v83, v211
	v_mov_b32_e32 v84, v212
	v_mov_b32_e32 v85, v213
	v_mov_b32_e32 v86, v214
	v_mov_b32_e32 v87, v215

; __device__ __forceinline__ unsigned cvt_pk_bf16(float lo, float hi) { const f32x2_t v = {lo, hi}; const bf16x2_t b = __builtin_convertvector(v, bf16x2_t); return __builtin_bit_cast(unsigned, b); }
;     __device__ __forceinline__ void operator()(const Acc& acc, const Unit& u, int wr, int wc, int fr, int fq) const {
;     ...
;                 if (u.pn <= 1) {
; #pragma unroll
;                     for (int n = 0; n < 2; ++n) { const int d = n * 16 + fq * 4;
;                         const f32x4 cs = *(const f32x4*)(rp + d), sn = *(const f32x4*)(rp + 32 + d);
;                         const f32x4 x1 = acc[ai][0][m][n], x2 = acc[ai][1][m][n];
;                         const f32x4 o1 = (x1 * cs - x2 * sn) * 0.125f, o2 = (x2 * cs + x1 * sn) * 0.125f;
;                         bf16_t* qp = Q + (size_t)row * 512 + (u.pn * 4 + wc) * 64 + d;
;                         *(u32x2*)qp = (u32x2){cvt_pk_bf16(o1[0], o1[1]), cvt_pk_bf16(o1[2], o1[3])};
;                         *(u32x2*)(qp + 32) = (u32x2){cvt_pk_bf16(o2[0], o2[1]), cvt_pk_bf16(o2[2], o2[3])}; }
.LBB0_607:
	s_and_b64 vcc, exec, s[46:47]
	s_cbranch_vccz .LBB0_609
	v_lshl_add_u64 v[90:91], v[144:145], 2, v[90:91]
	global_load_dwordx4 v[80:83], v[90:91], off offset:128
	global_load_dwordx4 v[84:87], v[90:91], off
	global_load_dwordx4 v[208:211], v[90:91], off offset:192
	global_load_dwordx4 v[212:215], v[90:91], off offset:64
	v_ashrrev_i32_e32 v89, 31, v88
	v_lshlrev_b64 v[88:89], 10, v[88:89]
	v_lshl_add_u64 v[88:89], s[14:15], 0, v[88:89]
	v_lshl_add_u64 v[88:89], s[44:45], 1, v[88:89]
	v_lshl_add_u64 v[88:89], v[144:145], 1, v[88:89]
	s_waitcnt vmcnt(0)
	v_pk_mul_f32 v[92:93], v[74:75], v[82:83]
	v_pk_mul_f32 v[94:95], v[72:73], v[80:81]
	v_pk_mul_f32 v[82:83], v[78:79], v[82:83]
	v_pk_mul_f32 v[80:81], v[76:77], v[80:81]
	v_pk_fma_f32 v[78:79], v[78:79], v[86:87], v[92:93] neg_lo:[0,0,1] neg_hi:[0,0,1]
	v_pk_fma_f32 v[76:77], v[76:77], v[84:85], v[94:95] neg_lo:[0,0,1] neg_hi:[0,0,1]
	v_pk_fma_f32 v[74:75], v[74:75], v[86:87], v[82:83]
	v_pk_fma_f32 v[72:73], v[72:73], v[84:85], v[80:81]
	v_pk_mul_f32 v[78:79], v[78:79], s[88:89] op_sel_hi:[1,0]
	v_pk_mul_f32 v[76:77], v[76:77], s[88:89] op_sel_hi:[1,0]
	v_pk_mul_f32 v[74:75], v[74:75], s[88:89] op_sel_hi:[1,0]
	v_pk_mul_f32 v[72:73], v[72:73], s[88:89] op_sel_hi:[1,0]
	v_cvt_pk_bf16_f32 v76, v76, v77
	v_cvt_pk_bf16_f32 v77, v78, v79
	v_cvt_pk_bf16_f32 v72, v72, v73
	v_cvt_pk_bf16_f32 v73, v74, v75
	global_store_dwordx2 v[88:89], v[76:77], off
	global_store_dwordx2 v[88:89], v[72:73], off offset:64
	v_pk_mul_f32 v[80:81], v[66:67], v[210:211]
	v_pk_mul_f32 v[82:83], v[64:65], v[208:209]
	v_pk_mul_f32 v[210:211], v[70:71], v[210:211]
	v_pk_mul_f32 v[208:209], v[68:69], v[208:209]
	v_pk_fma_f32 v[70:71], v[70:71], v[214:215], v[80:81] neg_lo:[0,0,1] neg_hi:[0,0,1]
	v_pk_fma_f32 v[68:69], v[68:69], v[212:213], v[82:83] neg_lo:[0,0,1] neg_hi:[0,0,1]
	v_pk_fma_f32 v[66:67], v[66:67], v[214:215], v[210:211]
	v_pk_fma_f32 v[64:65], v[64:65], v[212:213], v[208:209]
	v_pk_mul_f32 v[70:71], v[70:71], s[88:89] op_sel_hi:[1,0]
	v_pk_mul_f32 v[68:69], v[68:69], s[88:89] op_sel_hi:[1,0]
	v_pk_mul_f32 v[66:67], v[66:67], s[88:89] op_sel_hi:[1,0]
	v_pk_mul_f32 v[64:65], v[64:65], s[88:89] op_sel_hi:[1,0]
	v_cvt_pk_bf16_f32 v68, v68, v69
	v_cvt_pk_bf16_f32 v69, v70, v71
	v_cvt_pk_bf16_f32 v64, v64, v65
	v_cvt_pk_bf16_f32 v65, v66, v67
	global_store_dwordx2 v[88:89], v[68:69], off offset:32
	global_store_dwordx2 v[88:89], v[64:65], off offset:96
	v_mov_b32_e32 v72, v208
	v_mov_b32_e32 v73, v209
	v_mov_b32_e32 v74, v210
	v_mov_b32_e32 v75, v211
	v_mov_b32_e32 v76, v212
	v_mov_b32_e32 v77, v213
	v_mov_b32_e32 v78, v214
	v_mov_b32_e32 v79, v215

; __device__ __forceinline__ unsigned cvt_pk_bf16(float lo, float hi) { const f32x2_t v = {lo, hi}; const bf16x2_t b = __builtin_convertvector(v, bf16x2_t); return __builtin_bit_cast(unsigned, b); }
;     __device__ __forceinline__ void operator()(const Acc& acc, const Unit& u, int wr, int wc, int fr, int fq) const {
;     ...
;                     if (wc < 2) {
; #pragma unroll
;                         for (int n = 0; n < 2; ++n) { const int d = n * 16 + fq * 4;
;                             const f32x4 cs = *(const f32x4*)(rp + d), sn = *(const f32x4*)(rp + 32 + d);
;                             const f32x4 x1 = acc[ai][0][m][n], x2 = acc[ai][1][m][n];
;                             const f32x4 o1 = x1 * cs - x2 * sn, o2 = x2 * cs + x1 * sn;
;                             bf16_t* kp = Kb + (size_t)row * 128 + wc * 64 + d;
;                             *(u32x2*)kp = (u32x2){cvt_pk_bf16(o1[0], o1[1]), cvt_pk_bf16(o1[2], o1[3])};
;                             *(u32x2*)(kp + 32) = (u32x2){cvt_pk_bf16(o2[0], o2[1]), cvt_pk_bf16(o2[2], o2[3])};
;                             if (keep) { float* op = out + okoff + (orow * 2 + wc) * 64 + d; *(f32x4*)op = o1; *(f32x4*)(op + 32) = o2; } }
.LBB0_649:
	s_and_b64 vcc, exec, s[6:7]
	s_cbranch_vccz .LBB0_655
	v_lshl_add_u64 v[80:81], v[144:145], 2, v[74:75]
	global_load_dwordx4 v[68:71], v[80:81], off offset:128
	global_load_dwordx4 v[82:85], v[80:81], off
	global_load_dwordx4 v[208:211], v[80:81], off offset:192
	global_load_dwordx4 v[212:215], v[80:81], off offset:64
	v_ashrrev_i32_e32 v73, 31, v72
	v_lshl_add_u64 v[86:87], v[66:67], 0, v[64:65]
	v_lshlrev_b64 v[64:65], 8, v[72:73]
	v_lshl_add_u64 v[64:65], s[30:31], 0, v[64:65]
	v_lshl_add_u64 v[78:79], v[144:145], 1, v[64:65]
	s_waitcnt vmcnt(0)
	v_pk_mul_f32 v[64:65], v[58:59], v[70:71]
	v_pk_mul_f32 v[88:89], v[56:57], v[68:69]
	v_pk_mul_f32 v[70:71], v[62:63], v[70:71]
	v_pk_mul_f32 v[68:69], v[60:61], v[68:69]
	v_pk_fma_f32 v[66:67], v[62:63], v[84:85], v[64:65] neg_lo:[0,0,1] neg_hi:[0,0,1]
	v_pk_fma_f32 v[64:65], v[60:61], v[82:83], v[88:89] neg_lo:[0,0,1] neg_hi:[0,0,1]
	v_pk_fma_f32 v[70:71], v[58:59], v[84:85], v[70:71]
	v_pk_fma_f32 v[68:69], v[56:57], v[82:83], v[68:69]
	v_cvt_pk_bf16_f32 v82, v64, v65
	v_cvt_pk_bf16_f32 v83, v66, v67
	v_cvt_pk_bf16_f32 v84, v68, v69
	v_cvt_pk_bf16_f32 v85, v70, v71
	global_store_dwordx2 v[78:79], v[82:83], off
	global_store_dwordx2 v[78:79], v[84:85], off offset:64
	v_lshl_add_u64 v[82:83], v[86:87], 2, s[10:11]
	s_and_saveexec_b64 s[6:7], s[4:5]
	s_cbranch_execz .LBB0_652
	v_lshl_add_u64 v[84:85], v[82:83], 0, v[76:77]
	s_lshl_b32 s74, s66, 2
	v_lshl_add_u64 v[84:85], v[84:85], 0, s[74:75]
	v_lshl_add_u64 v[84:85], v[144:145], 2, v[84:85]
	global_store_dwordx4 v[84:85], v[64:67], off
	global_store_dwordx4 v[84:85], v[68:71], off offset:128
.LBB0_652:
	s_or_b64 exec, exec, s[6:7]
	v_pk_mul_f32 v[80:81], v[50:51], v[210:211]
	v_pk_mul_f32 v[84:85], v[48:49], v[208:209]
	v_pk_mul_f32 v[86:87], v[54:55], v[210:211]
	v_pk_mul_f32 v[88:89], v[52:53], v[208:209]
	v_pk_fma_f32 v[210:211], v[54:55], v[214:215], v[80:81] neg_lo:[0,0,1] neg_hi:[0,0,1]
	v_pk_fma_f32 v[208:209], v[52:53], v[212:213], v[84:85] neg_lo:[0,0,1] neg_hi:[0,0,1]
	v_pk_fma_f32 v[214:215], v[50:51], v[214:215], v[86:87]
	v_pk_fma_f32 v[212:213], v[48:49], v[212:213], v[88:89]
	v_cvt_pk_bf16_f32 v80, v208, v209
	v_cvt_pk_bf16_f32 v81, v210, v211
	v_cvt_pk_bf16_f32 v84, v212, v213
	v_cvt_pk_bf16_f32 v85, v214, v215
	global_store_dwordx2 v[78:79], v[80:81], off offset:32
	global_store_dwordx2 v[78:79], v[84:85], off offset:96
	s_and_saveexec_b64 s[6:7], s[4:5]
	s_cbranch_execz .LBB0_654
	v_lshl_add_u64 v[76:77], v[82:83], 0, v[76:77]
	s_lshl_b32 s74, s66, 2
	v_lshl_add_u64 v[76:77], v[76:77], 0, s[74:75]
	v_lshl_add_u64 v[76:77], v[144:145], 2, v[76:77]
	global_store_dwordx4 v[76:77], v[208:211], off offset:64
	global_store_dwordx4 v[76:77], v[212:215], off offset:192
.LBB0_654:
	s_or_b64 exec, exec, s[6:7]
	v_mov_b32_e32 v64, v208
	v_mov_b32_e32 v65, v209
	v_mov_b32_e32 v66, v210
	v_mov_b32_e32 v67, v211
	v_mov_b32_e32 v68, v212
	v_mov_b32_e32 v69, v213
	v_mov_b32_e32 v70, v214
	v_mov_b32_e32 v71, v215

; __device__ __forceinline__ unsigned cvt_pk_bf16(float lo, float hi) { const f32x2_t v = {lo, hi}; const bf16x2_t b = __builtin_convertvector(v, bf16x2_t); return __builtin_bit_cast(unsigned, b); }
;     __device__ __forceinline__ void operator()(const Acc& acc, const Unit& u, int wr, int wc, int fr, int fq) const {
;     ...
;                 if (u.pn <= 1) {
; #pragma unroll
;                     for (int n = 0; n < 2; ++n) { const int d = n * 16 + fq * 4;
;                         const f32x4 cs = *(const f32x4*)(rp + d), sn = *(const f32x4*)(rp + 32 + d);
;                         const f32x4 x1 = acc[ai][0][m][n], x2 = acc[ai][1][m][n];
;                         const f32x4 o1 = (x1 * cs - x2 * sn) * 0.125f, o2 = (x2 * cs + x1 * sn) * 0.125f;
;                         bf16_t* qp = Q + (size_t)row * 512 + (u.pn * 4 + wc) * 64 + d;
;                         *(u32x2*)qp = (u32x2){cvt_pk_bf16(o1[0], o1[1]), cvt_pk_bf16(o1[2], o1[3])};
;                         *(u32x2*)(qp + 32) = (u32x2){cvt_pk_bf16(o2[0], o2[1]), cvt_pk_bf16(o2[2], o2[3])}; }
.LBB0_656:
	s_and_b64 vcc, exec, s[46:47]
	s_cbranch_vccz .LBB0_658
	v_lshl_add_u64 v[74:75], v[144:145], 2, v[74:75]
	global_load_dwordx4 v[64:67], v[74:75], off offset:128
	global_load_dwordx4 v[68:71], v[74:75], off
	global_load_dwordx4 v[208:211], v[74:75], off offset:192
	global_load_dwordx4 v[212:215], v[74:75], off offset:64
	v_ashrrev_i32_e32 v73, 31, v72
	v_lshlrev_b64 v[72:73], 10, v[72:73]
	v_lshl_add_u64 v[72:73], s[14:15], 0, v[72:73]
	v_lshl_add_u64 v[72:73], s[44:45], 1, v[72:73]
	v_lshl_add_u64 v[72:73], v[144:145], 1, v[72:73]
	s_waitcnt vmcnt(0)
	v_pk_mul_f32 v[76:77], v[58:59], v[66:67]
	v_pk_mul_f32 v[78:79], v[56:57], v[64:65]
	v_pk_mul_f32 v[66:67], v[62:63], v[66:67]
	v_pk_mul_f32 v[64:65], v[60:61], v[64:65]
	v_pk_fma_f32 v[62:63], v[62:63], v[70:71], v[76:77] neg_lo:[0,0,1] neg_hi:[0,0,1]
	v_pk_fma_f32 v[60:61], v[60:61], v[68:69], v[78:79] neg_lo:[0,0,1] neg_hi:[0,0,1]
	v_pk_fma_f32 v[58:59], v[58:59], v[70:71], v[66:67]
	v_pk_fma_f32 v[56:57], v[56:57], v[68:69], v[64:65]
	v_pk_mul_f32 v[62:63], v[62:63], s[88:89] op_sel_hi:[1,0]
	v_pk_mul_f32 v[60:61], v[60:61], s[88:89] op_sel_hi:[1,0]
	v_pk_mul_f32 v[58:59], v[58:59], s[88:89] op_sel_hi:[1,0]
	v_pk_mul_f32 v[56:57], v[56:57], s[88:89] op_sel_hi:[1,0]
	v_cvt_pk_bf16_f32 v60, v60, v61
	v_cvt_pk_bf16_f32 v61, v62, v63
	v_cvt_pk_bf16_f32 v56, v56, v57
	v_cvt_pk_bf16_f32 v57, v58, v59
	global_store_dwordx2 v[72:73], v[60:61], off
	global_store_dwordx2 v[72:73], v[56:57], off offset:64
	v_pk_mul_f32 v[64:65], v[50:51], v[210:211]
	v_pk_mul_f32 v[66:67], v[48:49], v[208:209]
	v_pk_mul_f32 v[210:211], v[54:55], v[210:211]
	v_pk_mul_f32 v[208:209], v[52:53], v[208:209]
	v_pk_fma_f32 v[54:55], v[54:55], v[214:215], v[64:65] neg_lo:[0,0,1] neg_hi:[0,0,1]
	v_pk_fma_f32 v[52:53], v[52:53], v[212:213], v[66:67] neg_lo:[0,0,1] neg_hi:[0,0,1]
	v_pk_fma_f32 v[50:51], v[50:51], v[214:215], v[210:211]
	v_pk_fma_f32 v[48:49], v[48:49], v[212:213], v[208:209]
	v_pk_mul_f32 v[54:55], v[54:55], s[88:89] op_sel_hi:[1,0]
	v_pk_mul_f32 v[52:53], v[52:53], s[88:89] op_sel_hi:[1,0]
	v_pk_mul_f32 v[50:51], v[50:51], s[88:89] op_sel_hi:[1,0]
	v_pk_mul_f32 v[48:49], v[48:49], s[88:89] op_sel_hi:[1,0]
	v_cvt_pk_bf16_f32 v52, v52, v53
	v_cvt_pk_bf16_f32 v53, v54, v55
	v_cvt_pk_bf16_f32 v48, v48, v49
	v_cvt_pk_bf16_f32 v49, v50, v51
	global_store_dwordx2 v[72:73], v[52:53], off offset:32
	global_store_dwordx2 v[72:73], v[48:49], off offset:96
	v_mov_b32_e32 v56, v208
	v_mov_b32_e32 v57, v209
	v_mov_b32_e32 v58, v210
	v_mov_b32_e32 v59, v211
	v_mov_b32_e32 v60, v212
	v_mov_b32_e32 v61, v213
	v_mov_b32_e32 v62, v214
	v_mov_b32_e32 v63, v215

; __device__ __forceinline__ unsigned cvt_pk_bf16(float lo, float hi) { const f32x2_t v = {lo, hi}; const bf16x2_t b = __builtin_convertvector(v, bf16x2_t); return __builtin_bit_cast(unsigned, b); }
;     __device__ __forceinline__ void operator()(const Acc& acc, const Unit& u, int wr, int wc, int fr, int fq) const {
;     ...
;                     if (wc < 2) {
; #pragma unroll
;                         for (int n = 0; n < 2; ++n) { const int d = n * 16 + fq * 4;
;                             const f32x4 cs = *(const f32x4*)(rp + d), sn = *(const f32x4*)(rp + 32 + d);
;                             const f32x4 x1 = acc[ai][0][m][n], x2 = acc[ai][1][m][n];
;                             const f32x4 o1 = x1 * cs - x2 * sn, o2 = x2 * cs + x1 * sn;
;                             bf16_t* kp = Kb + (size_t)row * 128 + wc * 64 + d;
;                             *(u32x2*)kp = (u32x2){cvt_pk_bf16(o1[0], o1[1]), cvt_pk_bf16(o1[2], o1[3])};
;                             *(u32x2*)(kp + 32) = (u32x2){cvt_pk_bf16(o2[0], o2[1]), cvt_pk_bf16(o2[2], o2[3])};
;                             if (keep) { float* op = out + okoff + (orow * 2 + wc) * 64 + d; *(f32x4*)op = o1; *(f32x4*)(op + 32) = o2; } }
.LBB0_698:
	s_and_b64 vcc, exec, s[6:7]
	s_cbranch_vccz .LBB0_704
	v_lshl_add_u64 v[64:65], v[144:145], 2, v[58:59]
	global_load_dwordx4 v[52:55], v[64:65], off offset:128
	global_load_dwordx4 v[66:69], v[64:65], off
	global_load_dwordx4 v[208:211], v[64:65], off offset:192
	global_load_dwordx4 v[212:215], v[64:65], off offset:64
	v_ashrrev_i32_e32 v57, 31, v56
	v_lshl_add_u64 v[70:71], v[50:51], 0, v[48:49]
	v_lshlrev_b64 v[48:49], 8, v[56:57]
	v_lshl_add_u64 v[48:49], s[30:31], 0, v[48:49]
	v_lshl_add_u64 v[62:63], v[144:145], 1, v[48:49]
	s_waitcnt vmcnt(0)
	v_pk_mul_f32 v[48:49], v[42:43], v[54:55]
	v_pk_mul_f32 v[72:73], v[40:41], v[52:53]
	v_pk_mul_f32 v[54:55], v[46:47], v[54:55]
	v_pk_mul_f32 v[52:53], v[44:45], v[52:53]
	v_pk_fma_f32 v[50:51], v[46:47], v[68:69], v[48:49] neg_lo:[0,0,1] neg_hi:[0,0,1]
	v_pk_fma_f32 v[48:49], v[44:45], v[66:67], v[72:73] neg_lo:[0,0,1] neg_hi:[0,0,1]
	v_pk_fma_f32 v[54:55], v[42:43], v[68:69], v[54:55]
	v_pk_fma_f32 v[52:53], v[40:41], v[66:67], v[52:53]
	v_cvt_pk_bf16_f32 v66, v48, v49
	v_cvt_pk_bf16_f32 v67, v50, v51
	v_cvt_pk_bf16_f32 v68, v52, v53
	v_cvt_pk_bf16_f32 v69, v54, v55
	global_store_dwordx2 v[62:63], v[66:67], off
	global_store_dwordx2 v[62:63], v[68:69], off offset:64
	v_lshl_add_u64 v[66:67], v[70:71], 2, s[10:11]
	s_and_saveexec_b64 s[6:7], s[4:5]
	s_cbranch_execz .LBB0_701
	v_lshl_add_u64 v[68:69], v[66:67], 0, v[60:61]
	s_lshl_b32 s74, s66, 2
	v_lshl_add_u64 v[68:69], v[68:69], 0, s[74:75]
	v_lshl_add_u64 v[68:69], v[144:145], 2, v[68:69]
	global_store_dwordx4 v[68:69], v[48:51], off
	global_store_dwordx4 v[68:69], v[52:55], off offset:128
.LBB0_701:
	s_or_b64 exec, exec, s[6:7]
	v_pk_mul_f32 v[64:65], v[34:35], v[210:211]
	v_pk_mul_f32 v[68:69], v[32:33], v[208:209]
	v_pk_mul_f32 v[70:71], v[38:39], v[210:211]
	v_pk_mul_f32 v[72:73], v[36:37], v[208:209]
	v_pk_fma_f32 v[210:211], v[38:39], v[214:215], v[64:65] neg_lo:[0,0,1] neg_hi:[0,0,1]
	v_pk_fma_f32 v[208:209], v[36:37], v[212:213], v[68:69] neg_lo:[0,0,1] neg_hi:[0,0,1]
	v_pk_fma_f32 v[214:215], v[34:35], v[214:215], v[70:71]
	v_pk_fma_f32 v[212:213], v[32:33], v[212:213], v[72:73]
	v_cvt_pk_bf16_f32 v64, v208, v209
	v_cvt_pk_bf16_f32 v65, v210, v211
	v_cvt_pk_bf16_f32 v68, v212, v213
	v_cvt_pk_bf16_f32 v69, v214, v215
	global_store_dwordx2 v[62:63], v[64:65], off offset:32
	global_store_dwordx2 v[62:63], v[68:69], off offset:96
	s_and_saveexec_b64 s[6:7], s[4:5]
	s_cbranch_execz .LBB0_703
	v_lshl_add_u64 v[60:61], v[66:67], 0, v[60:61]
	s_lshl_b32 s74, s66, 2
	v_lshl_add_u64 v[60:61], v[60:61], 0, s[74:75]
	v_lshl_add_u64 v[60:61], v[144:145], 2, v[60:61]
	global_store_dwordx4 v[60:61], v[208:211], off offset:64
	global_store_dwordx4 v[60:61], v[212:215], off offset:192
.LBB0_703:
	s_or_b64 exec, exec, s[6:7]
	v_mov_b32_e32 v48, v208
	v_mov_b32_e32 v49, v209
	v_mov_b32_e32 v50, v210
	v_mov_b32_e32 v51, v211
	v_mov_b32_e32 v52, v212
	v_mov_b32_e32 v53, v213
	v_mov_b32_e32 v54, v214
	v_mov_b32_e32 v55, v215

; __device__ __forceinline__ unsigned cvt_pk_bf16(float lo, float hi) { const f32x2_t v = {lo, hi}; const bf16x2_t b = __builtin_convertvector(v, bf16x2_t); return __builtin_bit_cast(unsigned, b); }
;     __device__ __forceinline__ void operator()(const Acc& acc, const Unit& u, int wr, int wc, int fr, int fq) const {
;     ...
;                 if (u.pn <= 1) {
; #pragma unroll
;                     for (int n = 0; n < 2; ++n) { const int d = n * 16 + fq * 4;
;                         const f32x4 cs = *(const f32x4*)(rp + d), sn = *(const f32x4*)(rp + 32 + d);
;                         const f32x4 x1 = acc[ai][0][m][n], x2 = acc[ai][1][m][n];
;                         const f32x4 o1 = (x1 * cs - x2 * sn) * 0.125f, o2 = (x2 * cs + x1 * sn) * 0.125f;
;                         bf16_t* qp = Q + (size_t)row * 512 + (u.pn * 4 + wc) * 64 + d;
;                         *(u32x2*)qp = (u32x2){cvt_pk_bf16(o1[0], o1[1]), cvt_pk_bf16(o1[2], o1[3])};
;                         *(u32x2*)(qp + 32) = (u32x2){cvt_pk_bf16(o2[0], o2[1]), cvt_pk_bf16(o2[2], o2[3])}; }
.LBB0_705:
	s_and_b64 vcc, exec, s[46:47]
	s_cbranch_vccz .LBB0_707
	v_lshl_add_u64 v[58:59], v[144:145], 2, v[58:59]
	global_load_dwordx4 v[48:51], v[58:59], off offset:128
	global_load_dwordx4 v[52:55], v[58:59], off
	global_load_dwordx4 v[208:211], v[58:59], off offset:192
	global_load_dwordx4 v[212:215], v[58:59], off offset:64
	v_ashrrev_i32_e32 v57, 31, v56
	v_lshlrev_b64 v[56:57], 10, v[56:57]
	v_lshl_add_u64 v[56:57], s[14:15], 0, v[56:57]
	v_lshl_add_u64 v[56:57], s[44:45], 1, v[56:57]
	v_lshl_add_u64 v[56:57], v[144:145], 1, v[56:57]
	s_waitcnt vmcnt(0)
	v_pk_mul_f32 v[60:61], v[42:43], v[50:51]
	v_pk_mul_f32 v[62:63], v[40:41], v[48:49]
	v_pk_mul_f32 v[50:51], v[46:47], v[50:51]
	v_pk_mul_f32 v[48:49], v[44:45], v[48:49]
	v_pk_fma_f32 v[46:47], v[46:47], v[54:55], v[60:61] neg_lo:[0,0,1] neg_hi:[0,0,1]
	v_pk_fma_f32 v[44:45], v[44:45], v[52:53], v[62:63] neg_lo:[0,0,1] neg_hi:[0,0,1]
	v_pk_fma_f32 v[42:43], v[42:43], v[54:55], v[50:51]
	v_pk_fma_f32 v[40:41], v[40:41], v[52:53], v[48:49]
	v_pk_mul_f32 v[46:47], v[46:47], s[88:89] op_sel_hi:[1,0]
	v_pk_mul_f32 v[44:45], v[44:45], s[88:89] op_sel_hi:[1,0]
	v_pk_mul_f32 v[42:43], v[42:43], s[88:89] op_sel_hi:[1,0]
	v_pk_mul_f32 v[40:41], v[40:41], s[88:89] op_sel_hi:[1,0]
	v_cvt_pk_bf16_f32 v44, v44, v45
	v_cvt_pk_bf16_f32 v45, v46, v47
	v_cvt_pk_bf16_f32 v40, v40, v41
	v_cvt_pk_bf16_f32 v41, v42, v43
	global_store_dwordx2 v[56:57], v[44:45], off
	global_store_dwordx2 v[56:57], v[40:41], off offset:64
	v_pk_mul_f32 v[48:49], v[34:35], v[210:211]
	v_pk_mul_f32 v[50:51], v[32:33], v[208:209]
	v_pk_mul_f32 v[210:211], v[38:39], v[210:211]
	v_pk_mul_f32 v[208:209], v[36:37], v[208:209]
	v_pk_fma_f32 v[38:39], v[38:39], v[214:215], v[48:49] neg_lo:[0,0,1] neg_hi:[0,0,1]
	v_pk_fma_f32 v[36:37], v[36:37], v[212:213], v[50:51] neg_lo:[0,0,1] neg_hi:[0,0,1]
	v_pk_fma_f32 v[34:35], v[34:35], v[214:215], v[210:211]
	v_pk_fma_f32 v[32:33], v[32:33], v[212:213], v[208:209]
	v_pk_mul_f32 v[38:39], v[38:39], s[88:89] op_sel_hi:[1,0]
	v_pk_mul_f32 v[36:37], v[36:37], s[88:89] op_sel_hi:[1,0]
	v_pk_mul_f32 v[34:35], v[34:35], s[88:89] op_sel_hi:[1,0]
	v_pk_mul_f32 v[32:33], v[32:33], s[88:89] op_sel_hi:[1,0]
	v_cvt_pk_bf16_f32 v36, v36, v37
	v_cvt_pk_bf16_f32 v37, v38, v39
	v_cvt_pk_bf16_f32 v32, v32, v33
	v_cvt_pk_bf16_f32 v33, v34, v35
	global_store_dwordx2 v[56:57], v[36:37], off offset:32
	global_store_dwordx2 v[56:57], v[32:33], off offset:96
	v_mov_b32_e32 v40, v208
	v_mov_b32_e32 v41, v209
	v_mov_b32_e32 v42, v210
	v_mov_b32_e32 v43, v211
	v_mov_b32_e32 v44, v212
	v_mov_b32_e32 v45, v213
	v_mov_b32_e32 v46, v214
	v_mov_b32_e32 v47, v215

; __device__ __forceinline__ unsigned cvt_pk_bf16(float lo, float hi) { const f32x2_t v = {lo, hi}; const bf16x2_t b = __builtin_convertvector(v, bf16x2_t); return __builtin_bit_cast(unsigned, b); }
;     __device__ __forceinline__ void operator()(const Acc& acc, const Unit& u, int wr, int wc, int fr, int fq) const {
;     ...
;                     if (wc < 2) {
; #pragma unroll
;                         for (int n = 0; n < 2; ++n) { const int d = n * 16 + fq * 4;
;                             const f32x4 cs = *(const f32x4*)(rp + d), sn = *(const f32x4*)(rp + 32 + d);
;                             const f32x4 x1 = acc[ai][0][m][n], x2 = acc[ai][1][m][n];
;                             const f32x4 o1 = x1 * cs - x2 * sn, o2 = x2 * cs + x1 * sn;
;                             bf16_t* kp = Kb + (size_t)row * 128 + wc * 64 + d;
;                             *(u32x2*)kp = (u32x2){cvt_pk_bf16(o1[0], o1[1]), cvt_pk_bf16(o1[2], o1[3])};
;                             *(u32x2*)(kp + 32) = (u32x2){cvt_pk_bf16(o2[0], o2[1]), cvt_pk_bf16(o2[2], o2[3])};
;                             if (keep) { float* op = out + okoff + (orow * 2 + wc) * 64 + d; *(f32x4*)op = o1; *(f32x4*)(op + 32) = o2; } }
.LBB0_747:
	s_and_b64 vcc, exec, s[6:7]
	s_cbranch_vccz .LBB0_753
	v_lshl_add_u64 v[48:49], v[144:145], 2, v[42:43]
	global_load_dwordx4 v[36:39], v[48:49], off offset:128
	global_load_dwordx4 v[50:53], v[48:49], off
	global_load_dwordx4 v[208:211], v[48:49], off offset:192
	global_load_dwordx4 v[212:215], v[48:49], off offset:64
	v_ashrrev_i32_e32 v41, 31, v40
	v_lshl_add_u64 v[54:55], v[34:35], 0, v[32:33]
	v_lshlrev_b64 v[32:33], 8, v[40:41]
	v_lshl_add_u64 v[32:33], s[30:31], 0, v[32:33]
	v_lshl_add_u64 v[46:47], v[144:145], 1, v[32:33]
	s_waitcnt vmcnt(0)
	v_pk_mul_f32 v[32:33], v[26:27], v[38:39]
	v_pk_mul_f32 v[56:57], v[24:25], v[36:37]
	v_pk_mul_f32 v[38:39], v[30:31], v[38:39]
	v_pk_mul_f32 v[36:37], v[28:29], v[36:37]
	v_pk_fma_f32 v[34:35], v[30:31], v[52:53], v[32:33] neg_lo:[0,0,1] neg_hi:[0,0,1]
	v_pk_fma_f32 v[32:33], v[28:29], v[50:51], v[56:57] neg_lo:[0,0,1] neg_hi:[0,0,1]
	v_pk_fma_f32 v[38:39], v[26:27], v[52:53], v[38:39]
	v_pk_fma_f32 v[36:37], v[24:25], v[50:51], v[36:37]
	v_cvt_pk_bf16_f32 v50, v32, v33
	v_cvt_pk_bf16_f32 v51, v34, v35
	v_cvt_pk_bf16_f32 v52, v36, v37
	v_cvt_pk_bf16_f32 v53, v38, v39
	global_store_dwordx2 v[46:47], v[50:51], off
	global_store_dwordx2 v[46:47], v[52:53], off offset:64
	v_lshl_add_u64 v[50:51], v[54:55], 2, s[10:11]
	s_and_saveexec_b64 s[6:7], s[4:5]
	s_cbranch_execz .LBB0_750
	v_lshl_add_u64 v[52:53], v[50:51], 0, v[44:45]
	s_lshl_b32 s74, s66, 2
	v_lshl_add_u64 v[52:53], v[52:53], 0, s[74:75]
	v_lshl_add_u64 v[52:53], v[144:145], 2, v[52:53]
	global_store_dwordx4 v[52:53], v[32:35], off
	global_store_dwordx4 v[52:53], v[36:39], off offset:128
.LBB0_750:
	s_or_b64 exec, exec, s[6:7]
	v_pk_mul_f32 v[48:49], v[18:19], v[210:211]
	v_pk_mul_f32 v[52:53], v[16:17], v[208:209]
	v_pk_mul_f32 v[54:55], v[22:23], v[210:211]
	v_pk_mul_f32 v[56:57], v[20:21], v[208:209]
	v_pk_fma_f32 v[210:211], v[22:23], v[214:215], v[48:49] neg_lo:[0,0,1] neg_hi:[0,0,1]
	v_pk_fma_f32 v[208:209], v[20:21], v[212:213], v[52:53] neg_lo:[0,0,1] neg_hi:[0,0,1]
	v_pk_fma_f32 v[214:215], v[18:19], v[214:215], v[54:55]
	v_pk_fma_f32 v[212:213], v[16:17], v[212:213], v[56:57]
	v_cvt_pk_bf16_f32 v48, v208, v209
	v_cvt_pk_bf16_f32 v49, v210, v211
	v_cvt_pk_bf16_f32 v52, v212, v213
	v_cvt_pk_bf16_f32 v53, v214, v215
	global_store_dwordx2 v[46:47], v[48:49], off offset:32
	global_store_dwordx2 v[46:47], v[52:53], off offset:96
	s_and_saveexec_b64 s[6:7], s[4:5]
	s_cbranch_execz .LBB0_752
	v_lshl_add_u64 v[44:45], v[50:51], 0, v[44:45]
	s_lshl_b32 s74, s66, 2
	v_lshl_add_u64 v[44:45], v[44:45], 0, s[74:75]
	v_lshl_add_u64 v[44:45], v[144:145], 2, v[44:45]
	global_store_dwordx4 v[44:45], v[208:211], off offset:64
	global_store_dwordx4 v[44:45], v[212:215], off offset:192
.LBB0_752:
	s_or_b64 exec, exec, s[6:7]
	v_mov_b32_e32 v32, v208
	v_mov_b32_e32 v33, v209
	v_mov_b32_e32 v34, v210
	v_mov_b32_e32 v35, v211
	v_mov_b32_e32 v36, v212
	v_mov_b32_e32 v37, v213
	v_mov_b32_e32 v38, v214
	v_mov_b32_e32 v39, v215

; __device__ __forceinline__ unsigned cvt_pk_bf16(float lo, float hi) { const f32x2_t v = {lo, hi}; const bf16x2_t b = __builtin_convertvector(v, bf16x2_t); return __builtin_bit_cast(unsigned, b); }
;     __device__ __forceinline__ void operator()(const Acc& acc, const Unit& u, int wr, int wc, int fr, int fq) const {
;     ...
;                 if (u.pn <= 1) {
; #pragma unroll
;                     for (int n = 0; n < 2; ++n) { const int d = n * 16 + fq * 4;
;                         const f32x4 cs = *(const f32x4*)(rp + d), sn = *(const f32x4*)(rp + 32 + d);
;                         const f32x4 x1 = acc[ai][0][m][n], x2 = acc[ai][1][m][n];
;                         const f32x4 o1 = (x1 * cs - x2 * sn) * 0.125f, o2 = (x2 * cs + x1 * sn) * 0.125f;
;                         bf16_t* qp = Q + (size_t)row * 512 + (u.pn * 4 + wc) * 64 + d;
;                         *(u32x2*)qp = (u32x2){cvt_pk_bf16(o1[0], o1[1]), cvt_pk_bf16(o1[2], o1[3])};
;                         *(u32x2*)(qp + 32) = (u32x2){cvt_pk_bf16(o2[0], o2[1]), cvt_pk_bf16(o2[2], o2[3])}; }
.LBB0_754:
	s_and_b64 vcc, exec, s[46:47]
	s_cbranch_vccz .LBB0_756
	v_lshl_add_u64 v[42:43], v[144:145], 2, v[42:43]
	global_load_dwordx4 v[32:35], v[42:43], off offset:128
	global_load_dwordx4 v[36:39], v[42:43], off
	global_load_dwordx4 v[208:211], v[42:43], off offset:192
	global_load_dwordx4 v[212:215], v[42:43], off offset:64
	v_ashrrev_i32_e32 v41, 31, v40
	v_lshlrev_b64 v[40:41], 10, v[40:41]
	v_lshl_add_u64 v[40:41], s[14:15], 0, v[40:41]
	v_lshl_add_u64 v[40:41], s[44:45], 1, v[40:41]
	v_lshl_add_u64 v[40:41], v[144:145], 1, v[40:41]
	s_waitcnt vmcnt(0)
	v_pk_mul_f32 v[44:45], v[26:27], v[34:35]
	v_pk_mul_f32 v[46:47], v[24:25], v[32:33]
	v_pk_mul_f32 v[34:35], v[30:31], v[34:35]
	v_pk_mul_f32 v[32:33], v[28:29], v[32:33]
	v_pk_fma_f32 v[30:31], v[30:31], v[38:39], v[44:45] neg_lo:[0,0,1] neg_hi:[0,0,1]
	v_pk_fma_f32 v[28:29], v[28:29], v[36:37], v[46:47] neg_lo:[0,0,1] neg_hi:[0,0,1]
	v_pk_fma_f32 v[26:27], v[26:27], v[38:39], v[34:35]
	v_pk_fma_f32 v[24:25], v[24:25], v[36:37], v[32:33]
	v_pk_mul_f32 v[30:31], v[30:31], s[88:89] op_sel_hi:[1,0]
	v_pk_mul_f32 v[28:29], v[28:29], s[88:89] op_sel_hi:[1,0]
	v_pk_mul_f32 v[26:27], v[26:27], s[88:89] op_sel_hi:[1,0]
	v_pk_mul_f32 v[24:25], v[24:25], s[88:89] op_sel_hi:[1,0]
	v_cvt_pk_bf16_f32 v28, v28, v29
	v_cvt_pk_bf16_f32 v29, v30, v31
	v_cvt_pk_bf16_f32 v24, v24, v25
	v_cvt_pk_bf16_f32 v25, v26, v27
	global_store_dwordx2 v[40:41], v[28:29], off
	global_store_dwordx2 v[40:41], v[24:25], off offset:64
	v_pk_mul_f32 v[32:33], v[18:19], v[210:211]
	v_pk_mul_f32 v[34:35], v[16:17], v[208:209]
	v_pk_mul_f32 v[210:211], v[22:23], v[210:211]
	v_pk_mul_f32 v[208:209], v[20:21], v[208:209]
	v_pk_fma_f32 v[22:23], v[22:23], v[214:215], v[32:33] neg_lo:[0,0,1] neg_hi:[0,0,1]
	v_pk_fma_f32 v[20:21], v[20:21], v[212:213], v[34:35] neg_lo:[0,0,1] neg_hi:[0,0,1]
	v_pk_fma_f32 v[18:19], v[18:19], v[214:215], v[210:211]
	v_pk_fma_f32 v[16:17], v[16:17], v[212:213], v[208:209]
	v_pk_mul_f32 v[22:23], v[22:23], s[88:89] op_sel_hi:[1,0]
	v_pk_mul_f32 v[20:21], v[20:21], s[88:89] op_sel_hi:[1,0]
	v_pk_mul_f32 v[18:19], v[18:19], s[88:89] op_sel_hi:[1,0]
	v_pk_mul_f32 v[16:17], v[16:17], s[88:89] op_sel_hi:[1,0]
	v_cvt_pk_bf16_f32 v20, v20, v21
	v_cvt_pk_bf16_f32 v21, v22, v23
	v_cvt_pk_bf16_f32 v16, v16, v17
	v_cvt_pk_bf16_f32 v17, v18, v19
	global_store_dwordx2 v[40:41], v[20:21], off offset:32
	global_store_dwordx2 v[40:41], v[16:17], off offset:96
	v_mov_b32_e32 v24, v208
	v_mov_b32_e32 v25, v209
	v_mov_b32_e32 v26, v210
	v_mov_b32_e32 v27, v211
	v_mov_b32_e32 v28, v212
	v_mov_b32_e32 v29, v213
	v_mov_b32_e32 v30, v214
	v_mov_b32_e32 v31, v215

; __device__ __forceinline__ unsigned cvt_pk_bf16(float lo, float hi) { const f32x2_t v = {lo, hi}; const bf16x2_t b = __builtin_convertvector(v, bf16x2_t); return __builtin_bit_cast(unsigned, b); }
;     __device__ __forceinline__ void operator()(const Acc& acc, const Unit& u, int wr, int wc, int fr, int fq) const {
;     ...
;                     if (wc < 2) {
; #pragma unroll
;                         for (int n = 0; n < 2; ++n) { const int d = n * 16 + fq * 4;
;                             const f32x4 cs = *(const f32x4*)(rp + d), sn = *(const f32x4*)(rp + 32 + d);
;                             const f32x4 x1 = acc[ai][0][m][n], x2 = acc[ai][1][m][n];
;                             const f32x4 o1 = x1 * cs - x2 * sn, o2 = x2 * cs + x1 * sn;
;                             bf16_t* kp = Kb + (size_t)row * 128 + wc * 64 + d;
;                             *(u32x2*)kp = (u32x2){cvt_pk_bf16(o1[0], o1[1]), cvt_pk_bf16(o1[2], o1[3])};
;                             *(u32x2*)(kp + 32) = (u32x2){cvt_pk_bf16(o2[0], o2[1]), cvt_pk_bf16(o2[2], o2[3])};
;                             if (keep) { float* op = out + okoff + (orow * 2 + wc) * 64 + d; *(f32x4*)op = o1; *(f32x4*)(op + 32) = o2; } }
.LBB0_796:
	s_and_b64 vcc, exec, s[4:5]
	s_cbranch_vccz .LBB0_802
	v_lshl_add_u64 v[32:33], v[144:145], 2, v[26:27]
	global_load_dwordx4 v[20:23], v[32:33], off offset:128
	global_load_dwordx4 v[34:37], v[32:33], off
	global_load_dwordx4 v[208:211], v[32:33], off offset:192
	global_load_dwordx4 v[212:215], v[32:33], off offset:64
	v_ashrrev_i32_e32 v25, 31, v24
	v_lshl_add_u64 v[38:39], v[18:19], 0, v[16:17]
	v_lshlrev_b64 v[16:17], 8, v[24:25]
	v_lshl_add_u64 v[16:17], s[30:31], 0, v[16:17]
	v_lshl_add_u64 v[30:31], v[144:145], 1, v[16:17]
	s_waitcnt vmcnt(0)
	v_pk_mul_f32 v[16:17], v[10:11], v[22:23]
	v_pk_mul_f32 v[40:41], v[8:9], v[20:21]
	v_pk_mul_f32 v[22:23], v[14:15], v[22:23]
	v_pk_mul_f32 v[20:21], v[12:13], v[20:21]
	v_pk_fma_f32 v[18:19], v[14:15], v[36:37], v[16:17] neg_lo:[0,0,1] neg_hi:[0,0,1]
	v_pk_fma_f32 v[16:17], v[12:13], v[34:35], v[40:41] neg_lo:[0,0,1] neg_hi:[0,0,1]
	v_pk_fma_f32 v[22:23], v[10:11], v[36:37], v[22:23]
	v_pk_fma_f32 v[20:21], v[8:9], v[34:35], v[20:21]
	v_cvt_pk_bf16_f32 v34, v16, v17
	v_cvt_pk_bf16_f32 v35, v18, v19
	v_cvt_pk_bf16_f32 v36, v20, v21
	v_cvt_pk_bf16_f32 v37, v22, v23
	global_store_dwordx2 v[30:31], v[34:35], off
	global_store_dwordx2 v[30:31], v[36:37], off offset:64
	v_lshl_add_u64 v[34:35], v[38:39], 2, s[10:11]
	s_and_saveexec_b64 s[4:5], s[2:3]
	s_cbranch_execz .LBB0_799
	v_lshl_add_u64 v[36:37], v[34:35], 0, v[28:29]
	s_lshl_b32 s74, s66, 2
	v_lshl_add_u64 v[36:37], v[36:37], 0, s[74:75]
	v_lshl_add_u64 v[36:37], v[144:145], 2, v[36:37]
	global_store_dwordx4 v[36:37], v[16:19], off
	global_store_dwordx4 v[36:37], v[20:23], off offset:128
.LBB0_799:
	s_or_b64 exec, exec, s[4:5]
	v_pk_mul_f32 v[32:33], v[2:3], v[210:211]
	v_pk_mul_f32 v[36:37], v[0:1], v[208:209]
	v_pk_mul_f32 v[38:39], v[6:7], v[210:211]
	v_pk_mul_f32 v[40:41], v[4:5], v[208:209]
	v_pk_fma_f32 v[210:211], v[6:7], v[214:215], v[32:33] neg_lo:[0,0,1] neg_hi:[0,0,1]
	v_pk_fma_f32 v[208:209], v[4:5], v[212:213], v[36:37] neg_lo:[0,0,1] neg_hi:[0,0,1]
	v_pk_fma_f32 v[214:215], v[2:3], v[214:215], v[38:39]
	v_pk_fma_f32 v[212:213], v[0:1], v[212:213], v[40:41]
	v_cvt_pk_bf16_f32 v32, v208, v209
	v_cvt_pk_bf16_f32 v33, v210, v211
	v_cvt_pk_bf16_f32 v36, v212, v213
	v_cvt_pk_bf16_f32 v37, v214, v215
	global_store_dwordx2 v[30:31], v[32:33], off offset:32
	global_store_dwordx2 v[30:31], v[36:37], off offset:96
	s_and_saveexec_b64 s[4:5], s[2:3]
	s_cbranch_execz .LBB0_801
	v_lshl_add_u64 v[28:29], v[34:35], 0, v[28:29]
	s_lshl_b32 s74, s66, 2
	v_lshl_add_u64 v[28:29], v[28:29], 0, s[74:75]
	v_lshl_add_u64 v[28:29], v[144:145], 2, v[28:29]
	global_store_dwordx4 v[28:29], v[208:211], off offset:64
	global_store_dwordx4 v[28:29], v[212:215], off offset:192
.LBB0_801:
	s_or_b64 exec, exec, s[4:5]
	v_mov_b32_e32 v16, v208
	v_mov_b32_e32 v17, v209
	v_mov_b32_e32 v18, v210
	v_mov_b32_e32 v19, v211
	v_mov_b32_e32 v20, v212
	v_mov_b32_e32 v21, v213
	v_mov_b32_e32 v22, v214
	v_mov_b32_e32 v23, v215

; __device__ __forceinline__ unsigned cvt_pk_bf16(float lo, float hi) { const f32x2_t v = {lo, hi}; const bf16x2_t b = __builtin_convertvector(v, bf16x2_t); return __builtin_bit_cast(unsigned, b); }
;     __device__ __forceinline__ void operator()(const Acc& acc, const Unit& u, int wr, int wc, int fr, int fq) const {
;     ...
;                 if (u.pn <= 1) {
; #pragma unroll
;                     for (int n = 0; n < 2; ++n) { const int d = n * 16 + fq * 4;
;                         const f32x4 cs = *(const f32x4*)(rp + d), sn = *(const f32x4*)(rp + 32 + d);
;                         const f32x4 x1 = acc[ai][0][m][n], x2 = acc[ai][1][m][n];
;                         const f32x4 o1 = (x1 * cs - x2 * sn) * 0.125f, o2 = (x2 * cs + x1 * sn) * 0.125f;
;                         bf16_t* qp = Q + (size_t)row * 512 + (u.pn * 4 + wc) * 64 + d;
;                         *(u32x2*)qp = (u32x2){cvt_pk_bf16(o1[0], o1[1]), cvt_pk_bf16(o1[2], o1[3])};
;                         *(u32x2*)(qp + 32) = (u32x2){cvt_pk_bf16(o2[0], o2[1]), cvt_pk_bf16(o2[2], o2[3])}; }
.LBB0_804:
	s_and_b64 vcc, exec, s[2:3]
	s_cbranch_vccz .LBB0_803
	v_lshl_add_u64 v[26:27], v[144:145], 2, v[26:27]
	global_load_dwordx4 v[16:19], v[26:27], off offset:128
	global_load_dwordx4 v[20:23], v[26:27], off
	global_load_dwordx4 v[208:211], v[26:27], off offset:192
	global_load_dwordx4 v[212:215], v[26:27], off offset:64
	v_ashrrev_i32_e32 v25, 31, v24
	v_lshlrev_b64 v[24:25], 10, v[24:25]
	v_lshl_add_u64 v[24:25], s[14:15], 0, v[24:25]
	v_lshl_add_u64 v[24:25], s[44:45], 1, v[24:25]
	v_lshl_add_u64 v[24:25], v[144:145], 1, v[24:25]
	s_waitcnt vmcnt(0)
	v_pk_mul_f32 v[28:29], v[10:11], v[18:19]
	v_pk_mul_f32 v[30:31], v[8:9], v[16:17]
	v_pk_mul_f32 v[18:19], v[14:15], v[18:19]
	v_pk_mul_f32 v[16:17], v[12:13], v[16:17]
	v_pk_fma_f32 v[14:15], v[14:15], v[22:23], v[28:29] neg_lo:[0,0,1] neg_hi:[0,0,1]
	v_pk_fma_f32 v[12:13], v[12:13], v[20:21], v[30:31] neg_lo:[0,0,1] neg_hi:[0,0,1]
	v_pk_fma_f32 v[10:11], v[10:11], v[22:23], v[18:19]
	v_pk_fma_f32 v[8:9], v[8:9], v[20:21], v[16:17]
	v_pk_mul_f32 v[14:15], v[14:15], s[88:89] op_sel_hi:[1,0]
	v_pk_mul_f32 v[12:13], v[12:13], s[88:89] op_sel_hi:[1,0]
	v_pk_mul_f32 v[10:11], v[10:11], s[88:89] op_sel_hi:[1,0]
	v_pk_mul_f32 v[8:9], v[8:9], s[88:89] op_sel_hi:[1,0]
	v_cvt_pk_bf16_f32 v12, v12, v13
	v_cvt_pk_bf16_f32 v13, v14, v15
	v_cvt_pk_bf16_f32 v8, v8, v9
	v_cvt_pk_bf16_f32 v9, v10, v11
	global_store_dwordx2 v[24:25], v[12:13], off
	global_store_dwordx2 v[24:25], v[8:9], off offset:64
	v_pk_mul_f32 v[16:17], v[2:3], v[210:211]
	v_pk_mul_f32 v[18:19], v[0:1], v[208:209]
	v_pk_mul_f32 v[210:211], v[6:7], v[210:211]
	v_pk_mul_f32 v[208:209], v[4:5], v[208:209]
	v_pk_fma_f32 v[6:7], v[6:7], v[214:215], v[16:17] neg_lo:[0,0,1] neg_hi:[0,0,1]
	v_pk_fma_f32 v[4:5], v[4:5], v[212:213], v[18:19] neg_lo:[0,0,1] neg_hi:[0,0,1]
	v_pk_fma_f32 v[2:3], v[2:3], v[214:215], v[210:211]
	v_pk_fma_f32 v[0:1], v[0:1], v[212:213], v[208:209]
	v_pk_mul_f32 v[6:7], v[6:7], s[88:89] op_sel_hi:[1,0]
	v_pk_mul_f32 v[4:5], v[4:5], s[88:89] op_sel_hi:[1,0]
	v_pk_mul_f32 v[2:3], v[2:3], s[88:89] op_sel_hi:[1,0]
	v_pk_mul_f32 v[0:1], v[0:1], s[88:89] op_sel_hi:[1,0]
	v_cvt_pk_bf16_f32 v4, v4, v5
	v_cvt_pk_bf16_f32 v5, v6, v7
	v_cvt_pk_bf16_f32 v0, v0, v1
	v_cvt_pk_bf16_f32 v1, v2, v3
	global_store_dwordx2 v[24:25], v[4:5], off offset:32
	global_store_dwordx2 v[24:25], v[0:1], off offset:96
	s_andn2_b64 vcc, exec, s[0:1]
	s_mov_b64 s[0:1], -1
	s_cbranch_vccnz .LBB0_402
	v_mov_b32_e32 v8, v208
	v_mov_b32_e32 v9, v209
	v_mov_b32_e32 v10, v210
	v_mov_b32_e32 v11, v211
	v_mov_b32_e32 v12, v212
	v_mov_b32_e32 v13, v213
	v_mov_b32_e32 v14, v214
	v_mov_b32_e32 v15, v215
